# P0 first-norm loop: software prefetch of next two rows into a spare VGPR bank (v160-191), staged vmcnt ladder removed, back-edge vmcnt(8)
# speedup vs baseline: 1.0050x; 1.0029x over previous
; template <bool HB, bool FINAL>
; __device__ __forceinline__ void norm_rows(const void* src, const bf16* y, float ys, bf16* hdst, const float* gain, bf16* xn, float* fout, float* fstage, int gw, int NGW, int lane) {
;     ...
;     for (int m0 = gw; m0 < T; m0 += 2 * NGW) {
;         f32x4 v[2][4]; u32x2 yw[2][4];
; #pragma unroll
;         for (int r = 0; r < 2; ++r) { const int m = m0 + r * NGW;
;             if (HB) { const u32x2* hr = (const u32x2*)((const bf16*)src + (size_t)m * D) + lane;
; #pragma unroll
;                 for (int j = 0; j < 4; ++j) { const u32x2 w = hr[64 * j]; v[r][j] = (f32x4){__uint_as_float(w.x << 16), __uint_as_float(w.x & 0xffff0000u), __uint_as_float(w.y << 16), __uint_as_float(w.y & 0xffff0000u)}; }
;             } else { const f32x4* xr = (const f32x4*)((const float*)src + (size_t)m * D) + lane;
; #pragma unroll
;                 for (int j = 0; j < 4; ++j) v[r][j] = xr[64 * j]; }
;             if (y) { const u32x2* yr = (const u32x2*)(y + (size_t)m * D) + lane;
; #pragma unroll
;                 for (int j = 0; j < 4; ++j) yw[r][j] = yr[64 * j]; } }
.LBB0_40:
	s_ashr_i32 s7, s6, 31
	s_add_i32 s10, s6, s33
	s_lshl_b64 s[4:5], s[6:7], 12
	s_ashr_i32 s11, s10, 31
	v_lshl_add_u64 v[192:193], v[50:51], 0, s[4:5]
	s_lshl_b64 s[4:5], s[10:11], 12
	v_lshl_add_u64 v[194:195], v[50:51], 0, s[4:5]
	global_load_dwordx4 v[160:163], v[192:193], off
	global_load_dwordx4 v[164:167], v[192:193], off offset:1024
	global_load_dwordx4 v[168:171], v[192:193], off offset:2048
	global_load_dwordx4 v[172:175], v[192:193], off offset:3072
	global_load_dwordx4 v[176:179], v[194:195], off
	global_load_dwordx4 v[180:183], v[194:195], off offset:1024
	global_load_dwordx4 v[184:187], v[194:195], off offset:2048
	global_load_dwordx4 v[188:191], v[194:195], off offset:3072
	s_waitcnt vmcnt(0)
.LQ_copy:
	s_ashr_i32 s7, s6, 31
	s_add_i32 s10, s6, s33
	s_ashr_i32 s11, s10, 31
	v_mov_b32_e32 v26, v160
	v_mov_b32_e32 v27, v161
	v_mov_b32_e32 v28, v162
	v_mov_b32_e32 v29, v163
	v_mov_b32_e32 v22, v164
	v_mov_b32_e32 v23, v165
	v_mov_b32_e32 v24, v166
	v_mov_b32_e32 v25, v167
	v_mov_b32_e32 v34, v168
	v_mov_b32_e32 v35, v169
	v_mov_b32_e32 v36, v170
	v_mov_b32_e32 v37, v171
	v_mov_b32_e32 v30, v172
	v_mov_b32_e32 v31, v173
	v_mov_b32_e32 v32, v174
	v_mov_b32_e32 v33, v175
	v_mov_b32_e32 v38, v176
	v_mov_b32_e32 v39, v177
	v_mov_b32_e32 v40, v178
	v_mov_b32_e32 v41, v179
	v_mov_b32_e32 v18, v180
	v_mov_b32_e32 v19, v181
	v_mov_b32_e32 v20, v182
	v_mov_b32_e32 v21, v183
	v_mov_b32_e32 v46, v184
	v_mov_b32_e32 v47, v185
	v_mov_b32_e32 v48, v186
	v_mov_b32_e32 v49, v187
	v_mov_b32_e32 v42, v188
	v_mov_b32_e32 v43, v189
	v_mov_b32_e32 v44, v190
	v_mov_b32_e32 v45, v191
	s_add_i32 s12, s10, s33
	s_cmp_lt_i32 s12, 0x8000
	s_cbranch_scc0 .LQ_C
	s_ashr_i32 s13, s12, 31
	s_add_i32 s14, s12, s33
	s_ashr_i32 s15, s14, 31
	s_lshl_b64 s[4:5], s[12:13], 12
	v_lshl_add_u64 v[192:193], v[50:51], 0, s[4:5]
	s_lshl_b64 s[4:5], s[14:15], 12
	v_lshl_add_u64 v[194:195], v[50:51], 0, s[4:5]
	global_load_dwordx4 v[160:163], v[192:193], off
	global_load_dwordx4 v[164:167], v[192:193], off offset:1024
	global_load_dwordx4 v[168:171], v[192:193], off offset:2048
	global_load_dwordx4 v[172:175], v[192:193], off offset:3072
	global_load_dwordx4 v[176:179], v[194:195], off
	global_load_dwordx4 v[180:183], v[194:195], off offset:1024
	global_load_dwordx4 v[184:187], v[194:195], off offset:2048
	global_load_dwordx4 v[188:191], v[194:195], off offset:3072
; __device__ __forceinline__ unsigned cvt_pk_bf16(float lo, float hi) { f32x2_t v = {lo, hi}; bf16x2_t b = __builtin_convertvector(v, bf16x2_t); return __builtin_bit_cast(unsigned, b); }
; template <bool HB, bool FINAL>
; __device__ __forceinline__ void norm_rows(const void* src, const bf16* y, float ys, bf16* hdst, const float* gain, bf16* xn, float* fout, float* fstage, int gw, int NGW, int lane) {
;     ...
;         float s[2];
; #pragma unroll
;         for (int r = 0; r < 2; ++r) { s[r] = 0.f;
;             if (y) {
; #pragma unroll
;                 for (int j = 0; j < 4; ++j) { const u32x2 w = yw[r][j];
;                     v[r][j].x += ys * __uint_as_float(w.x << 16); v[r][j].y += ys * __uint_as_float(w.x & 0xffff0000u); v[r][j].z += ys * __uint_as_float(w.y << 16); v[r][j].w += ys * __uint_as_float(w.y & 0xffff0000u); } }
; #pragma unroll
;             for (int j = 0; j < 4; ++j) s[r] += (v[r][j].x * v[r][j].x + v[r][j].y * v[r][j].y) + (v[r][j].z * v[r][j].z + v[r][j].w * v[r][j].w); }
; #pragma unroll
;         for (int o = 1; o < 64; o <<= 1) { s[0] += __shfl_xor(s[0], o); s[1] += __shfl_xor(s[1], o); }
; #pragma unroll
;         for (int r = 0; r < 2; ++r) { const int m = m0 + r * NGW; const float rstd = rsqrtf(s[r] * (1.f / D) + EPS);
;             if (!FINAL && hdst) { u32x2* hr = (u32x2*)(hdst + (size_t)m * D) + lane;
; #pragma unroll
;                 for (int j = 0; j < 4; ++j) { u32x2 w; w.x = cvt_pk_bf16(v[r][j].x, v[r][j].y); w.y = cvt_pk_bf16(v[r][j].z, v[r][j].w); hr[64 * j] = w; } }
;             if (FINAL) { f32x4* o = (f32x4*)((m >= T / 2 ? fout : fstage) + (size_t)m * D) + lane;
; #pragma unroll
;                 for (int j = 0; j < 4; ++j) o[64 * j] = v[r][j] * rstd * gv[j];
;             } else { u32x2* o = (u32x2*)(xn + (size_t)m * D) + lane;
; #pragma unroll
;                 for (int j = 0; j < 4; ++j) { const f32x4 q = v[r][j] * rstd * gv[j]; u32x2 w; w.x = cvt_pk_bf16(q.x, q.y); w.y = cvt_pk_bf16(q.z, q.w); o[64 * j] = w; } } }
.LQ_C:
	s_lshl_b64 s[4:5], s[6:7], 11
	v_pk_mul_f32 v[62:63], v[28:29], v[28:29]
	v_pk_mul_f32 v[64:65], v[26:27], v[26:27]
	v_pk_mul_f32 v[66:67], v[24:25], v[24:25]
	v_pk_mul_f32 v[68:69], v[22:23], v[22:23]
	v_pk_mov_b32 v[74:75], v[64:65], v[62:63] op_sel:[1,0]
	v_mov_b32_e32 v65, v63
	v_pk_mov_b32 v[62:63], v[68:69], v[66:67] op_sel:[1,0]
	v_mov_b32_e32 v69, v67
	v_pk_mul_f32 v[66:67], v[40:41], v[40:41]
	v_pk_mul_f32 v[76:77], v[38:39], v[38:39]
	v_pk_mul_f32 v[78:79], v[20:21], v[20:21]
	v_pk_mul_f32 v[80:81], v[18:19], v[18:19]
	v_pk_add_f32 v[62:63], v[62:63], v[68:69]
	v_pk_mov_b32 v[68:69], v[76:77], v[66:67] op_sel:[1,0]
	v_mov_b32_e32 v77, v67
	v_pk_mov_b32 v[66:67], v[80:81], v[78:79] op_sel:[1,0]
	v_mov_b32_e32 v81, v79
	v_mul_f32_e32 v70, v35, v35
	v_mul_f32_e32 v72, v37, v37
	v_mul_f32_e32 v83, v33, v33
	v_mul_f32_e32 v85, v30, v30
	v_mul_f32_e32 v82, v47, v47
	v_mul_f32_e32 v84, v49, v49
	v_pk_add_f32 v[64:65], v[74:75], v[64:65]
	v_pk_add_f32 v[68:69], v[68:69], v[76:77]
	v_pk_add_f32 v[66:67], v[66:67], v[80:81]
	v_mul_f32_e32 v61, v32, v32
	v_mul_f32_e32 v86, v31, v31
	v_pk_fma_f32 v[70:71], v[34:35], v[34:35], v[70:71] op_sel_hi:[1,1,0]
	v_pk_fma_f32 v[72:73], v[36:37], v[36:37], v[72:73] op_sel_hi:[1,1,0]
	v_mul_f32_e32 v87, v44, v44
	v_mul_f32_e32 v88, v45, v45
	v_mul_f32_e32 v89, v42, v42
	v_mul_f32_e32 v90, v43, v43
	v_pk_fma_f32 v[74:75], v[46:47], v[46:47], v[82:83] op_sel_hi:[1,1,0]
	v_pk_fma_f32 v[78:79], v[48:49], v[48:49], v[84:85] op_sel_hi:[1,1,0]
	v_pk_add_f32 v[64:65], v[64:65], v[64:65] op_sel:[0,1] op_sel_hi:[1,0]
	v_pk_add_f32 v[62:63], v[62:63], v[62:63] op_sel:[0,1] op_sel_hi:[1,0]
	v_pk_add_f32 v[68:69], v[68:69], v[68:69] op_sel:[0,1] op_sel_hi:[1,0]
	v_pk_add_f32 v[66:67], v[66:67], v[66:67] op_sel:[0,1] op_sel_hi:[1,0]
	v_mov_b32_e32 v71, v61
	v_mov_b32_e32 v73, v83
	v_mov_b32_e32 v75, v87
	v_mov_b32_e32 v79, v88
	v_mov_b32_e32 v65, v85
	v_mov_b32_e32 v63, v86
	v_mov_b32_e32 v69, v89
	v_mov_b32_e32 v67, v90
	v_pk_add_f32 v[70:71], v[70:71], v[72:73]
	v_pk_add_f32 v[72:73], v[74:75], v[78:79]
	v_pk_add_f32 v[62:63], v[64:65], v[62:63]
	v_pk_add_f32 v[64:65], v[68:69], v[66:67]
	v_pk_add_f32 v[62:63], v[62:63], v[70:71]
	v_pk_add_f32 v[64:65], v[64:65], v[72:73]
	v_mov_b32_e32 v67, v62
	v_mov_b32_e32 v66, v64
	v_mov_b32_e32 v62, v65
	v_pk_add_f32 v[62:63], v[66:67], v[62:63]
	ds_bpermute_b32 v65, v1, v63
	ds_bpermute_b32 v64, v1, v62
	v_lshl_add_u64 v[66:67], v[52:53], 0, s[4:5]
	s_lshl_b64 s[4:5], s[10:11], 11
	s_waitcnt lgkmcnt(0)
	v_pk_add_f32 v[62:63], v[62:63], v[64:65]
	ds_bpermute_b32 v65, v56, v63
	ds_bpermute_b32 v64, v56, v62
	s_waitcnt lgkmcnt(0)
	v_pk_add_f32 v[62:63], v[62:63], v[64:65]
	ds_bpermute_b32 v65, v57, v63
	ds_bpermute_b32 v64, v57, v62
	s_waitcnt lgkmcnt(0)
	v_pk_add_f32 v[62:63], v[62:63], v[64:65]
	ds_bpermute_b32 v65, v58, v63
	ds_bpermute_b32 v64, v58, v62
	s_waitcnt lgkmcnt(0)
	v_pk_add_f32 v[62:63], v[62:63], v[64:65]
	ds_bpermute_b32 v65, v59, v63
	ds_bpermute_b32 v64, v59, v62
	s_waitcnt lgkmcnt(0)
	v_pk_add_f32 v[62:63], v[62:63], v[64:65]
	ds_bpermute_b32 v65, v60, v63
	ds_bpermute_b32 v64, v60, v62
	s_waitcnt lgkmcnt(0)
	v_pk_add_f32 v[62:63], v[62:63], v[64:65]
	s_nop 0
	v_pk_fma_f32 v[62:63], v[62:63], s[8:9], v[54:55] op_sel_hi:[1,0,0]
	s_nop 0
	v_mul_f32_e32 v61, 0x4b800000, v63
	v_mul_f32_e32 v64, 0x4b800000, v62
	v_cmp_gt_f32_e32 vcc, s1, v63
	v_cmp_gt_f32_e64 s[6:7], s1, v62
	s_nop 0
	v_cndmask_b32_e32 v61, v63, v61, vcc
	v_cndmask_b32_e64 v62, v62, v64, s[6:7]
	v_rsq_f32_e32 v61, v61
	v_rsq_f32_e32 v65, v62
	v_lshl_add_u64 v[62:63], v[52:53], 0, s[4:5]
	v_mul_f32_e32 v64, 0x45800000, v61
	v_mul_f32_e32 v68, 0x45800000, v65
	v_cndmask_b32_e32 v64, v61, v64, vcc
	v_cndmask_b32_e64 v68, v65, v68, s[6:7]
	v_pk_mul_f32 v[26:27], v[26:27], v[64:65] op_sel_hi:[1,0]
	v_pk_mul_f32 v[28:29], v[28:29], v[64:65] op_sel_hi:[1,0]
	v_pk_mul_f32 v[18:19], v[18:19], v[68:69] op_sel_hi:[1,0]
	v_pk_mul_f32 v[20:21], v[20:21], v[68:69] op_sel_hi:[1,0]
	v_pk_mul_f32 v[22:23], v[22:23], v[64:65] op_sel_hi:[1,0]
	v_pk_mul_f32 v[24:25], v[24:25], v[64:65] op_sel_hi:[1,0]
	v_pk_mul_f32 v[34:35], v[34:35], v[64:65] op_sel_hi:[1,0]
	v_pk_mul_f32 v[36:37], v[36:37], v[64:65] op_sel_hi:[1,0]
	v_pk_mul_f32 v[30:31], v[30:31], v[64:65] op_sel_hi:[1,0]
	v_pk_mul_f32 v[32:33], v[32:33], v[64:65] op_sel_hi:[1,0]
	v_pk_mul_f32 v[38:39], v[38:39], v[68:69] op_sel_hi:[1,0]
	v_pk_mul_f32 v[40:41], v[40:41], v[68:69] op_sel_hi:[1,0]
	v_pk_mul_f32 v[28:29], v[4:5], v[28:29]
	v_pk_mul_f32 v[26:27], v[2:3], v[26:27]
	v_pk_mul_f32 v[20:21], v[8:9], v[20:21]
	v_pk_mul_f32 v[18:19], v[6:7], v[18:19]
	v_pk_mul_f32 v[24:25], v[8:9], v[24:25]
	v_pk_mul_f32 v[22:23], v[6:7], v[22:23]
	v_pk_mul_f32 v[36:37], v[12:13], v[36:37]
	v_pk_mul_f32 v[34:35], v[10:11], v[34:35]
	v_pk_mul_f32 v[32:33], v[16:17], v[32:33]
	v_pk_mul_f32 v[30:31], v[14:15], v[30:31]
	v_pk_mul_f32 v[40:41], v[4:5], v[40:41]
	v_pk_mul_f32 v[38:39], v[2:3], v[38:39]
	v_cvt_pk_bf16_f32 v26, v26, v27
	v_cvt_pk_bf16_f32 v27, v28, v29
	v_cvt_pk_bf16_f32 v18, v18, v19
	v_cvt_pk_bf16_f32 v19, v20, v21
	v_cvt_pk_bf16_f32 v22, v22, v23
	v_cvt_pk_bf16_f32 v23, v24, v25
	v_cvt_pk_bf16_f32 v24, v34, v35
	v_cvt_pk_bf16_f32 v25, v36, v37
	v_cvt_pk_bf16_f32 v28, v30, v31
	v_cvt_pk_bf16_f32 v29, v32, v33
	v_cvt_pk_bf16_f32 v30, v38, v39
	v_cvt_pk_bf16_f32 v31, v40, v41
	global_store_dwordx2 v[66:67], v[26:27], off
	global_store_dwordx2 v[66:67], v[22:23], off offset:512
	global_store_dwordx2 v[66:67], v[24:25], off offset:1024
	global_store_dwordx2 v[66:67], v[28:29], off offset:1536
	global_store_dwordx2 v[62:63], v[30:31], off
	global_store_dwordx2 v[62:63], v[18:19], off offset:512
	v_pk_mul_f32 v[18:19], v[46:47], v[68:69] op_sel_hi:[1,0]
	v_pk_mul_f32 v[20:21], v[48:49], v[68:69] op_sel_hi:[1,0]
	v_pk_mul_f32 v[18:19], v[10:11], v[18:19]
	v_pk_mul_f32 v[20:21], v[12:13], v[20:21]
	v_cvt_pk_bf16_f32 v18, v18, v19
	v_cvt_pk_bf16_f32 v19, v20, v21
	global_store_dwordx2 v[62:63], v[18:19], off offset:1024
	v_pk_mul_f32 v[18:19], v[42:43], v[68:69] op_sel_hi:[1,0]
	v_pk_mul_f32 v[20:21], v[44:45], v[68:69] op_sel_hi:[1,0]
	v_pk_mul_f32 v[18:19], v[14:15], v[18:19]
	v_pk_mul_f32 v[20:21], v[16:17], v[20:21]
	s_add_i32 s6, s10, s33
	v_cvt_pk_bf16_f32 v18, v18, v19
	v_cvt_pk_bf16_f32 v19, v20, v21
	s_cmp_lt_i32 s6, 0x8000
	global_store_dwordx2 v[62:63], v[18:19], off offset:1536
	s_cbranch_scc0 .LQ_exit
	s_waitcnt vmcnt(8)
	s_branch .LQ_copy
.LQ_exit:
.LBB0_41:
	v_lshrrev_b32_e32 v1, 20, v0
	v_lshrrev_b32_e32 v0, 10, v0
	v_or_b32_e32 v0, v0, v1
	s_movk_i32 s1, 0x3ff
	v_and_or_b32 v0, v0, s1, v143
	v_cmp_eq_u32_e32 vcc, 0, v0
	s_barrier
	s_mov_b64 s[6:7], exec
